# phase 0: filter-MLP items rebalanced toward the 64 blocks that have no adaLN GEMV item (20 items each vs 4)
# speedup vs baseline: 1.0016x; 1.0008x over previous
; DI void phase_prep(const P& p, int bid, int nb) {
;     ...
;   {
;     float* zb = (float*)(g_smem + 16384); float* ha = zb + 8 * 36; float* hb = ha + 8 * 64;
;     bf16_t* HDN = (bf16_t*)(p.ws + OFF_HDN);
;     const int tl = tid >> 6, j = tid & 63;
;     for (int it = bid; it < 2048; it += nb) {
;       const int t = it * 8 + tl;
;       if (j < 33) { float v; if (j == 0) v = (float)t * (1.f / 16383.f); else { int i = (j - 1) & 15; float fr = 1e-4f + (float)i * ((15.f - 1e-4f) / 15.f); float turns = fr * ((float)t * (1.f / 16384.f)); turns -= floorf(turns);
;           v = (j <= 16) ? __builtin_amdgcn_cosf(turns) : -__builtin_amdgcn_sinf(turns); } zb[tl * 36 + j] = v; }
;       __syncthreads();
;       float acc = p.emb_b[j];
; #pragma unroll 3
;       for (int i = 0; i < 33; ++i) acc += zb[tl * 36 + i] * p.emb_w[i * 64 + j];
.LBB0_27:
	s_cmpk_gt_i32 s2, 0x7ff
	s_cbranch_scc1 .LBB0_42
	s_load_dwordx16 s[16:31], s[0:1], 0x80
	v_and_b32_e32 v1, 0x3ff, v0
	v_and_b32_e32 v215, 63, v1
	v_lshrrev_b32_e32 v2, 6, v1
	v_lshlrev_b32_e32 v216, 2, v215
	v_readfirstlane_b32 s9, v2
	v_lshlrev_b32_e32 v217, 1, v215
	v_add_u32_e32 v3, -1, v215
	v_and_b32_e32 v3, 15, v3
	v_cvt_f32_ubyte0_e32 v3, v3
	v_mov_b32_e32 v214, 0x38d1b717
	v_fmac_f32_e32 v214, 0x3f7fff90, v3
	v_cmp_ne_u32_e64 s[4:5], 0, v215
	v_cmp_gt_u32_e64 s[6:7], 17, v215
	s_waitcnt lgkmcnt(0)
	s_add_u32 s14, s20, 0x0
	s_addc_u32 s15, s21, 0
	global_load_dword v40, v216, s[14:15]
	global_load_dword v41, v216, s[14:15] offset:256
	global_load_dword v42, v216, s[14:15] offset:512
	global_load_dword v43, v216, s[14:15] offset:768
	global_load_dword v44, v216, s[14:15] offset:1024
	global_load_dword v45, v216, s[14:15] offset:1280
	global_load_dword v46, v216, s[14:15] offset:1536
	global_load_dword v47, v216, s[14:15] offset:1792
	global_load_dword v48, v216, s[14:15] offset:2048
	global_load_dword v49, v216, s[14:15] offset:2304
	global_load_dword v50, v216, s[14:15] offset:2560
	global_load_dword v51, v216, s[14:15] offset:2816
	global_load_dword v52, v216, s[14:15] offset:3072
	global_load_dword v53, v216, s[14:15] offset:3328
	global_load_dword v54, v216, s[14:15] offset:3584
	global_load_dword v55, v216, s[14:15] offset:3840
	s_add_u32 s14, s20, 0x1000
	s_addc_u32 s15, s21, 0
	global_load_dword v56, v216, s[14:15]
	global_load_dword v57, v216, s[14:15] offset:256
	global_load_dword v58, v216, s[14:15] offset:512
	global_load_dword v59, v216, s[14:15] offset:768
	global_load_dword v60, v216, s[14:15] offset:1024
	global_load_dword v61, v216, s[14:15] offset:1280
	global_load_dword v62, v216, s[14:15] offset:1536
	global_load_dword v63, v216, s[14:15] offset:1792
	global_load_dword v64, v216, s[14:15] offset:2048
	global_load_dword v65, v216, s[14:15] offset:2304
	global_load_dword v66, v216, s[14:15] offset:2560
	global_load_dword v67, v216, s[14:15] offset:2816
	global_load_dword v68, v216, s[14:15] offset:3072
	global_load_dword v69, v216, s[14:15] offset:3328
	global_load_dword v70, v216, s[14:15] offset:3584
	global_load_dword v71, v216, s[14:15] offset:3840
	s_add_u32 s14, s20, 0x2000
	s_addc_u32 s15, s21, 0
	global_load_dword v72, v216, s[14:15]
	s_add_u32 s14, s24, 0x0
	s_addc_u32 s15, s25, 0
	global_load_dword v80, v216, s[14:15]
	global_load_dword v81, v216, s[14:15] offset:256
	global_load_dword v82, v216, s[14:15] offset:512
	global_load_dword v83, v216, s[14:15] offset:768
	global_load_dword v84, v216, s[14:15] offset:1024
	global_load_dword v85, v216, s[14:15] offset:1280
	global_load_dword v86, v216, s[14:15] offset:1536
	global_load_dword v87, v216, s[14:15] offset:1792
	global_load_dword v88, v216, s[14:15] offset:2048
	global_load_dword v89, v216, s[14:15] offset:2304
	global_load_dword v90, v216, s[14:15] offset:2560
	global_load_dword v91, v216, s[14:15] offset:2816
	global_load_dword v92, v216, s[14:15] offset:3072
	global_load_dword v93, v216, s[14:15] offset:3328
	global_load_dword v94, v216, s[14:15] offset:3584
	global_load_dword v95, v216, s[14:15] offset:3840
	s_add_u32 s14, s24, 0x1000
	s_addc_u32 s15, s25, 0
	global_load_dword v96, v216, s[14:15]
	global_load_dword v97, v216, s[14:15] offset:256
	global_load_dword v98, v216, s[14:15] offset:512
	global_load_dword v99, v216, s[14:15] offset:768
	global_load_dword v100, v216, s[14:15] offset:1024
	global_load_dword v101, v216, s[14:15] offset:1280
	global_load_dword v102, v216, s[14:15] offset:1536
	global_load_dword v103, v216, s[14:15] offset:1792
	global_load_dword v104, v216, s[14:15] offset:2048
	global_load_dword v105, v216, s[14:15] offset:2304
	global_load_dword v106, v216, s[14:15] offset:2560
	global_load_dword v107, v216, s[14:15] offset:2816
	global_load_dword v108, v216, s[14:15] offset:3072
	global_load_dword v109, v216, s[14:15] offset:3328
	global_load_dword v110, v216, s[14:15] offset:3584
	global_load_dword v111, v216, s[14:15] offset:3840
	s_add_u32 s14, s24, 0x2000
	s_addc_u32 s15, s25, 0
	global_load_dword v112, v216, s[14:15]
	global_load_dword v113, v216, s[14:15] offset:256
	global_load_dword v114, v216, s[14:15] offset:512
	global_load_dword v115, v216, s[14:15] offset:768
	global_load_dword v116, v216, s[14:15] offset:1024
	global_load_dword v117, v216, s[14:15] offset:1280
	global_load_dword v118, v216, s[14:15] offset:1536
	global_load_dword v119, v216, s[14:15] offset:1792
	global_load_dword v120, v216, s[14:15] offset:2048
	global_load_dword v121, v216, s[14:15] offset:2304
	global_load_dword v122, v216, s[14:15] offset:2560
	global_load_dword v123, v216, s[14:15] offset:2816
	global_load_dword v124, v216, s[14:15] offset:3072
	global_load_dword v125, v216, s[14:15] offset:3328
	global_load_dword v126, v216, s[14:15] offset:3584
	global_load_dword v127, v216, s[14:15] offset:3840
	s_add_u32 s14, s24, 0x3000
	s_addc_u32 s15, s25, 0
	global_load_dword v128, v216, s[14:15]
; DI void phase_prep(const P& p, int bid, int nb) {
;     ...
;   {
;     float* zb = (float*)(g_smem + 16384); float* ha = zb + 8 * 36; float* hb = ha + 8 * 64;
;     bf16_t* HDN = (bf16_t*)(p.ws + OFF_HDN);
;     const int tl = tid >> 6, j = tid & 63;
;     for (int it = bid; it < 2048; it += nb) {
;       const int t = it * 8 + tl;
;       if (j < 33) { float v; if (j == 0) v = (float)t * (1.f / 16383.f); else { int i = (j - 1) & 15; float fr = 1e-4f + (float)i * ((15.f - 1e-4f) / 15.f); float turns = fr * ((float)t * (1.f / 16384.f)); turns -= floorf(turns);
;           v = (j <= 16) ? __builtin_amdgcn_cosf(turns) : -__builtin_amdgcn_sinf(turns); } zb[tl * 36 + j] = v; }
;       __syncthreads();
;       float acc = p.emb_b[j];
; #pragma unroll 3
;       for (int i = 0; i < 33; ++i) acc += zb[tl * 36 + i] * p.emb_w[i * 64 + j];
	global_load_dword v129, v216, s[14:15] offset:256
	global_load_dword v130, v216, s[14:15] offset:512
	global_load_dword v131, v216, s[14:15] offset:768
	global_load_dword v132, v216, s[14:15] offset:1024
	global_load_dword v133, v216, s[14:15] offset:1280
	global_load_dword v134, v216, s[14:15] offset:1536
	global_load_dword v135, v216, s[14:15] offset:1792
	global_load_dword v136, v216, s[14:15] offset:2048
	global_load_dword v137, v216, s[14:15] offset:2304
	global_load_dword v138, v216, s[14:15] offset:2560
	global_load_dword v139, v216, s[14:15] offset:2816
	global_load_dword v140, v216, s[14:15] offset:3072
	global_load_dword v141, v216, s[14:15] offset:3328
	global_load_dword v142, v216, s[14:15] offset:3584
	global_load_dword v143, v216, s[14:15] offset:3840
	s_add_u32 s24, s24, 0x4000
	s_addc_u32 s25, s25, 0
	s_add_u32 s14, s24, 0x0
	s_addc_u32 s15, s25, 0
	global_load_dword v144, v216, s[14:15]
	global_load_dword v145, v216, s[14:15] offset:256
	global_load_dword v146, v216, s[14:15] offset:512
	global_load_dword v147, v216, s[14:15] offset:768
	global_load_dword v148, v216, s[14:15] offset:1024
	global_load_dword v149, v216, s[14:15] offset:1280
	global_load_dword v150, v216, s[14:15] offset:1536
	global_load_dword v151, v216, s[14:15] offset:1792
	global_load_dword v152, v216, s[14:15] offset:2048
	global_load_dword v153, v216, s[14:15] offset:2304
	global_load_dword v154, v216, s[14:15] offset:2560
	global_load_dword v155, v216, s[14:15] offset:2816
	global_load_dword v156, v216, s[14:15] offset:3072
	global_load_dword v157, v216, s[14:15] offset:3328
	global_load_dword v158, v216, s[14:15] offset:3584
	global_load_dword v159, v216, s[14:15] offset:3840
	s_add_u32 s14, s24, 0x1000
	s_addc_u32 s15, s25, 0
	global_load_dword v160, v216, s[14:15]
	global_load_dword v161, v216, s[14:15] offset:256
	global_load_dword v162, v216, s[14:15] offset:512
	global_load_dword v163, v216, s[14:15] offset:768
	global_load_dword v164, v216, s[14:15] offset:1024
	global_load_dword v165, v216, s[14:15] offset:1280
	global_load_dword v166, v216, s[14:15] offset:1536
	global_load_dword v167, v216, s[14:15] offset:1792
	global_load_dword v168, v216, s[14:15] offset:2048
	global_load_dword v169, v216, s[14:15] offset:2304
	global_load_dword v170, v216, s[14:15] offset:2560
	global_load_dword v171, v216, s[14:15] offset:2816
	global_load_dword v172, v216, s[14:15] offset:3072
	global_load_dword v173, v216, s[14:15] offset:3328
	global_load_dword v174, v216, s[14:15] offset:3584
	global_load_dword v175, v216, s[14:15] offset:3840
	s_add_u32 s14, s24, 0x2000
	s_addc_u32 s15, s25, 0
	global_load_dword v176, v216, s[14:15]
	global_load_dword v177, v216, s[14:15] offset:256
	global_load_dword v178, v216, s[14:15] offset:512
	global_load_dword v179, v216, s[14:15] offset:768
	global_load_dword v180, v216, s[14:15] offset:1024
	global_load_dword v181, v216, s[14:15] offset:1280
	global_load_dword v182, v216, s[14:15] offset:1536
	global_load_dword v183, v216, s[14:15] offset:1792
	global_load_dword v184, v216, s[14:15] offset:2048
	global_load_dword v185, v216, s[14:15] offset:2304
	global_load_dword v186, v216, s[14:15] offset:2560
	global_load_dword v187, v216, s[14:15] offset:2816
	global_load_dword v188, v216, s[14:15] offset:3072
	global_load_dword v189, v216, s[14:15] offset:3328
	global_load_dword v190, v216, s[14:15] offset:3584
	global_load_dword v191, v216, s[14:15] offset:3840
	s_add_u32 s14, s24, 0x3000
	s_addc_u32 s15, s25, 0
	global_load_dword v192, v216, s[14:15]
	global_load_dword v193, v216, s[14:15] offset:256
	global_load_dword v194, v216, s[14:15] offset:512
	global_load_dword v195, v216, s[14:15] offset:768
	global_load_dword v196, v216, s[14:15] offset:1024
	global_load_dword v197, v216, s[14:15] offset:1280
	global_load_dword v198, v216, s[14:15] offset:1536
	global_load_dword v199, v216, s[14:15] offset:1792
	global_load_dword v200, v216, s[14:15] offset:2048
	global_load_dword v201, v216, s[14:15] offset:2304
	global_load_dword v202, v216, s[14:15] offset:2560
	global_load_dword v203, v216, s[14:15] offset:2816
	global_load_dword v204, v216, s[14:15] offset:3072
	global_load_dword v205, v216, s[14:15] offset:3328
	global_load_dword v206, v216, s[14:15] offset:3584
	global_load_dword v207, v216, s[14:15] offset:3840
	global_load_dword v208, v216, s[22:23]
	global_load_dword v209, v216, s[26:27]
	global_load_dword v210, v216, s[26:27] offset:256
	global_load_dword v211, v216, s[28:29]
	global_load_dword v212, v216, s[28:29] offset:256
	global_load_dword v213, v216, s[28:29] offset:512
	s_add_u32 s14, s84, 0x100000
	s_addc_u32 s15, s85, 0
	s_mov_b32 s3, s2
	s_mov_b32 vcc_hi, s88
	s_movk_i32 vcc_lo, 0x800
	s_cmp_lg_u32 s88, 0x100
	s_cbranch_scc1 .Lmlp_rng
	s_mov_b32 vcc_hi, 1
	s_cmp_lt_u32 s2, 0xc0
	s_cbranch_scc0 .Lmlp_big
	s_lshl_b32 s3, s2, 2
	s_add_u32 vcc_lo, s3, 4
	s_branch .Lmlp_rng
.Lmlp_big:
	s_sub_u32 s3, s2, 0xc0
	s_mul_i32 s3, s3, 20
	s_add_u32 s3, s3, 0x300
	s_add_u32 vcc_lo, s3, 20

; DI void phase_prep(const P& p, int bid, int nb) {
;     ...
;     const int tl = tid >> 6, j = tid & 63;
;     for (int it = bid; it < 2048; it += nb) {
;       const int t = it * 8 + tl;
;       if (j < 33) { float v; if (j == 0) v = (float)t * (1.f / 16383.f); else { int i = (j - 1) & 15; float fr = 1e-4f + (float)i * ((15.f - 1e-4f) / 15.f); float turns = fr * ((float)t * (1.f / 16384.f)); turns -= floorf(turns);
;           v = (j <= 16) ? __builtin_amdgcn_cosf(turns) : -__builtin_amdgcn_sinf(turns); } zb[tl * 36 + j] = v; }
;       __syncthreads();
;       float acc = p.emb_b[j];
; #pragma unroll 3
;       for (int i = 0; i < 33; ++i) acc += zb[tl * 36 + i] * p.emb_w[i * 64 + j];
;       ha[tl * 64 + j] = __sinf(p.freq[j] * acc);
;       __syncthreads();
;       acc = p.mlp_b[j];
; #pragma unroll 8
;       for (int i = 0; i < 64; ++i) acc += ha[tl * 64 + i] * p.mlp_w[i * 64 + j];
;       hb[tl * 64 + j] = __sinf(p.freq[64 + j] * acc);
.Lmlp_loop:
	s_lshl_b32 s8, s3, 3
	s_add_u32 s8, s8, s9
	v_cvt_f32_i32_e32 v218, s8
	v_mul_f32_e32 v219, 0x38800000, v218
	v_mul_f32_e32 v220, v214, v219
	v_floor_f32_e32 v220, v220
	v_fma_f32 v219, v214, v219, -v220
	v_cos_f32_e32 v221, v219
	v_sin_f32_e64 v222, -v219
	s_nop 0
	v_cndmask_b32_e64 v223, v222, v221, s[6:7]
	v_mul_f32_e32 v220, 0x38800200, v218
	v_cndmask_b32_e64 v223, v220, v223, s[4:5]
	v_mov_b32_e32 v224, v208
	s_nop 1
	v_readlane_b32 s16, v223, 0
	v_readlane_b32 s17, v223, 1
	v_readlane_b32 s18, v223, 2
	v_readlane_b32 s19, v223, 3
	v_readlane_b32 s20, v223, 4
	v_readlane_b32 s21, v223, 5
	v_readlane_b32 s22, v223, 6
	v_readlane_b32 s23, v223, 7
	v_readlane_b32 s24, v223, 8
	v_readlane_b32 s25, v223, 9
	v_readlane_b32 s26, v223, 10
	v_readlane_b32 s27, v223, 11
	v_readlane_b32 s28, v223, 12
	v_readlane_b32 s29, v223, 13
	v_readlane_b32 s30, v223, 14
	v_readlane_b32 s31, v223, 15
	v_fmac_f32_e32 v224, s16, v40
	v_fmac_f32_e32 v224, s17, v41
	v_fmac_f32_e32 v224, s18, v42
	v_fmac_f32_e32 v224, s19, v43
	v_fmac_f32_e32 v224, s20, v44
	v_fmac_f32_e32 v224, s21, v45
	v_fmac_f32_e32 v224, s22, v46
	v_fmac_f32_e32 v224, s23, v47
	v_fmac_f32_e32 v224, s24, v48
	v_fmac_f32_e32 v224, s25, v49
	v_fmac_f32_e32 v224, s26, v50
	v_fmac_f32_e32 v224, s27, v51
	v_fmac_f32_e32 v224, s28, v52
	v_fmac_f32_e32 v224, s29, v53
	v_fmac_f32_e32 v224, s30, v54
	v_fmac_f32_e32 v224, s31, v55
	v_readlane_b32 s16, v223, 16
	v_readlane_b32 s17, v223, 17
	v_readlane_b32 s18, v223, 18
	v_readlane_b32 s19, v223, 19
	v_readlane_b32 s20, v223, 20
	v_readlane_b32 s21, v223, 21
	v_readlane_b32 s22, v223, 22
	v_readlane_b32 s23, v223, 23
	v_readlane_b32 s24, v223, 24
	v_readlane_b32 s25, v223, 25
	v_readlane_b32 s26, v223, 26
	v_readlane_b32 s27, v223, 27
	v_readlane_b32 s28, v223, 28
	v_readlane_b32 s29, v223, 29
	v_readlane_b32 s30, v223, 30
	v_readlane_b32 s31, v223, 31
	v_fmac_f32_e32 v224, s16, v56
	v_fmac_f32_e32 v224, s17, v57
	v_fmac_f32_e32 v224, s18, v58
	v_fmac_f32_e32 v224, s19, v59
	v_fmac_f32_e32 v224, s20, v60
	v_fmac_f32_e32 v224, s21, v61
	v_fmac_f32_e32 v224, s22, v62
	v_fmac_f32_e32 v224, s23, v63
	v_fmac_f32_e32 v224, s24, v64
	v_fmac_f32_e32 v224, s25, v65
	v_fmac_f32_e32 v224, s26, v66
	v_fmac_f32_e32 v224, s27, v67
	v_fmac_f32_e32 v224, s28, v68
	v_fmac_f32_e32 v224, s29, v69
	v_fmac_f32_e32 v224, s30, v70
	v_fmac_f32_e32 v224, s31, v71
	v_readlane_b32 s16, v223, 32
	s_nop 1
	v_fmac_f32_e32 v224, s16, v72
	v_mul_f32_e32 v224, v224, v211
	v_mul_f32_e32 v224, 0.15915494, v224
	v_sin_f32_e32 v225, v224
	v_mov_b32_e32 v224, v209
	s_nop 1
	v_readlane_b32 s16, v225, 0
	v_readlane_b32 s17, v225, 1
	v_readlane_b32 s18, v225, 2
	v_readlane_b32 s19, v225, 3
	v_readlane_b32 s20, v225, 4
	v_readlane_b32 s21, v225, 5
	v_readlane_b32 s22, v225, 6
	v_readlane_b32 s23, v225, 7
	v_readlane_b32 s24, v225, 8
	v_readlane_b32 s25, v225, 9
	v_readlane_b32 s26, v225, 10
	v_readlane_b32 s27, v225, 11
	v_readlane_b32 s28, v225, 12
	v_readlane_b32 s29, v225, 13
	v_readlane_b32 s30, v225, 14
	v_readlane_b32 s31, v225, 15
	v_fmac_f32_e32 v224, s16, v80
	v_fmac_f32_e32 v224, s17, v81
	v_fmac_f32_e32 v224, s18, v82
	v_fmac_f32_e32 v224, s19, v83
	v_fmac_f32_e32 v224, s20, v84
	v_fmac_f32_e32 v224, s21, v85
	v_fmac_f32_e32 v224, s22, v86
	v_fmac_f32_e32 v224, s23, v87
	v_fmac_f32_e32 v224, s24, v88
	v_fmac_f32_e32 v224, s25, v89
	v_fmac_f32_e32 v224, s26, v90
	v_fmac_f32_e32 v224, s27, v91
	v_fmac_f32_e32 v224, s28, v92
	v_fmac_f32_e32 v224, s29, v93
	v_fmac_f32_e32 v224, s30, v94
	v_fmac_f32_e32 v224, s31, v95
	v_readlane_b32 s16, v225, 16
	v_readlane_b32 s17, v225, 17
	v_readlane_b32 s18, v225, 18
	v_readlane_b32 s19, v225, 19
	v_readlane_b32 s20, v225, 20
	v_readlane_b32 s21, v225, 21
	v_readlane_b32 s22, v225, 22
	v_readlane_b32 s23, v225, 23
	v_readlane_b32 s24, v225, 24
	v_readlane_b32 s25, v225, 25
	v_readlane_b32 s26, v225, 26
	v_readlane_b32 s27, v225, 27
	v_readlane_b32 s28, v225, 28
	v_readlane_b32 s29, v225, 29
	v_readlane_b32 s30, v225, 30
	v_readlane_b32 s31, v225, 31
	v_fmac_f32_e32 v224, s16, v96
	v_fmac_f32_e32 v224, s17, v97
	v_fmac_f32_e32 v224, s18, v98
	v_fmac_f32_e32 v224, s19, v99
	v_fmac_f32_e32 v224, s20, v100
	v_fmac_f32_e32 v224, s21, v101
	v_fmac_f32_e32 v224, s22, v102
	v_fmac_f32_e32 v224, s23, v103
	v_fmac_f32_e32 v224, s24, v104
	v_fmac_f32_e32 v224, s25, v105
	v_fmac_f32_e32 v224, s26, v106
	v_fmac_f32_e32 v224, s27, v107
	v_fmac_f32_e32 v224, s28, v108
	v_fmac_f32_e32 v224, s29, v109
	v_fmac_f32_e32 v224, s30, v110
	v_fmac_f32_e32 v224, s31, v111
	v_readlane_b32 s16, v225, 32
	v_readlane_b32 s17, v225, 33
	v_readlane_b32 s18, v225, 34
	v_readlane_b32 s19, v225, 35
	v_readlane_b32 s20, v225, 36
	v_readlane_b32 s21, v225, 37
	v_readlane_b32 s22, v225, 38
	v_readlane_b32 s23, v225, 39
	v_readlane_b32 s24, v225, 40
	v_readlane_b32 s25, v225, 41
	v_readlane_b32 s26, v225, 42
	v_readlane_b32 s27, v225, 43
	v_readlane_b32 s28, v225, 44
	v_readlane_b32 s29, v225, 45
	v_readlane_b32 s30, v225, 46
	v_readlane_b32 s31, v225, 47
	v_fmac_f32_e32 v224, s16, v112
	v_fmac_f32_e32 v224, s17, v113
	v_fmac_f32_e32 v224, s18, v114
	v_fmac_f32_e32 v224, s19, v115
	v_fmac_f32_e32 v224, s20, v116
	v_fmac_f32_e32 v224, s21, v117
	v_fmac_f32_e32 v224, s22, v118
	v_fmac_f32_e32 v224, s23, v119
	v_fmac_f32_e32 v224, s24, v120
	v_fmac_f32_e32 v224, s25, v121
	v_fmac_f32_e32 v224, s26, v122
	v_fmac_f32_e32 v224, s27, v123
	v_fmac_f32_e32 v224, s28, v124
	v_fmac_f32_e32 v224, s29, v125
; DI void phase_prep(const P& p, int bid, int nb) {
;     ...
;       acc = p.mlp_b[j];
; #pragma unroll 8
;       for (int i = 0; i < 64; ++i) acc += ha[tl * 64 + i] * p.mlp_w[i * 64 + j];
;       hb[tl * 64 + j] = __sinf(p.freq[64 + j] * acc);
;       __syncthreads();
;       acc = p.mlp_b[64 + j];
; #pragma unroll 8
;       for (int i = 0; i < 64; ++i) acc += hb[tl * 64 + i] * p.mlp_w[4096 + i * 64 + j];
;       HDN[(size_t)t * 64 + j] = f2bf(__sinf(p.freq[128 + j] * acc));
;       __syncthreads();
;     }
	v_fmac_f32_e32 v224, s30, v126
	v_fmac_f32_e32 v224, s31, v127
	v_readlane_b32 s16, v225, 48
	v_readlane_b32 s17, v225, 49
	v_readlane_b32 s18, v225, 50
	v_readlane_b32 s19, v225, 51
	v_readlane_b32 s20, v225, 52
	v_readlane_b32 s21, v225, 53
	v_readlane_b32 s22, v225, 54
	v_readlane_b32 s23, v225, 55
	v_readlane_b32 s24, v225, 56
	v_readlane_b32 s25, v225, 57
	v_readlane_b32 s26, v225, 58
	v_readlane_b32 s27, v225, 59
	v_readlane_b32 s28, v225, 60
	v_readlane_b32 s29, v225, 61
	v_readlane_b32 s30, v225, 62
	v_readlane_b32 s31, v225, 63
	v_fmac_f32_e32 v224, s16, v128
	v_fmac_f32_e32 v224, s17, v129
	v_fmac_f32_e32 v224, s18, v130
	v_fmac_f32_e32 v224, s19, v131
	v_fmac_f32_e32 v224, s20, v132
	v_fmac_f32_e32 v224, s21, v133
	v_fmac_f32_e32 v224, s22, v134
	v_fmac_f32_e32 v224, s23, v135
	v_fmac_f32_e32 v224, s24, v136
	v_fmac_f32_e32 v224, s25, v137
	v_fmac_f32_e32 v224, s26, v138
	v_fmac_f32_e32 v224, s27, v139
	v_fmac_f32_e32 v224, s28, v140
	v_fmac_f32_e32 v224, s29, v141
	v_fmac_f32_e32 v224, s30, v142
	v_fmac_f32_e32 v224, s31, v143
	v_mul_f32_e32 v224, v224, v212
	v_mul_f32_e32 v224, 0.15915494, v224
	v_sin_f32_e32 v223, v224
	v_mov_b32_e32 v224, v210
	s_nop 1
	v_readlane_b32 s16, v223, 0
	v_readlane_b32 s17, v223, 1
	v_readlane_b32 s18, v223, 2
	v_readlane_b32 s19, v223, 3
	v_readlane_b32 s20, v223, 4
	v_readlane_b32 s21, v223, 5
	v_readlane_b32 s22, v223, 6
	v_readlane_b32 s23, v223, 7
	v_readlane_b32 s24, v223, 8
	v_readlane_b32 s25, v223, 9
	v_readlane_b32 s26, v223, 10
	v_readlane_b32 s27, v223, 11
	v_readlane_b32 s28, v223, 12
	v_readlane_b32 s29, v223, 13
	v_readlane_b32 s30, v223, 14
	v_readlane_b32 s31, v223, 15
	v_fmac_f32_e32 v224, s16, v144
	v_fmac_f32_e32 v224, s17, v145
	v_fmac_f32_e32 v224, s18, v146
	v_fmac_f32_e32 v224, s19, v147
	v_fmac_f32_e32 v224, s20, v148
	v_fmac_f32_e32 v224, s21, v149
	v_fmac_f32_e32 v224, s22, v150
	v_fmac_f32_e32 v224, s23, v151
	v_fmac_f32_e32 v224, s24, v152
	v_fmac_f32_e32 v224, s25, v153
	v_fmac_f32_e32 v224, s26, v154
	v_fmac_f32_e32 v224, s27, v155
	v_fmac_f32_e32 v224, s28, v156
	v_fmac_f32_e32 v224, s29, v157
	v_fmac_f32_e32 v224, s30, v158
	v_fmac_f32_e32 v224, s31, v159
	v_readlane_b32 s16, v223, 16
	v_readlane_b32 s17, v223, 17
	v_readlane_b32 s18, v223, 18
	v_readlane_b32 s19, v223, 19
	v_readlane_b32 s20, v223, 20
	v_readlane_b32 s21, v223, 21
	v_readlane_b32 s22, v223, 22
	v_readlane_b32 s23, v223, 23
	v_readlane_b32 s24, v223, 24
	v_readlane_b32 s25, v223, 25
	v_readlane_b32 s26, v223, 26
	v_readlane_b32 s27, v223, 27
	v_readlane_b32 s28, v223, 28
	v_readlane_b32 s29, v223, 29
	v_readlane_b32 s30, v223, 30
	v_readlane_b32 s31, v223, 31
	v_fmac_f32_e32 v224, s16, v160
	v_fmac_f32_e32 v224, s17, v161
	v_fmac_f32_e32 v224, s18, v162
	v_fmac_f32_e32 v224, s19, v163
	v_fmac_f32_e32 v224, s20, v164
	v_fmac_f32_e32 v224, s21, v165
	v_fmac_f32_e32 v224, s22, v166
	v_fmac_f32_e32 v224, s23, v167
	v_fmac_f32_e32 v224, s24, v168
	v_fmac_f32_e32 v224, s25, v169
	v_fmac_f32_e32 v224, s26, v170
	v_fmac_f32_e32 v224, s27, v171
	v_fmac_f32_e32 v224, s28, v172
	v_fmac_f32_e32 v224, s29, v173
	v_fmac_f32_e32 v224, s30, v174
	v_fmac_f32_e32 v224, s31, v175
	v_readlane_b32 s16, v223, 32
	v_readlane_b32 s17, v223, 33
	v_readlane_b32 s18, v223, 34
	v_readlane_b32 s19, v223, 35
	v_readlane_b32 s20, v223, 36
	v_readlane_b32 s21, v223, 37
	v_readlane_b32 s22, v223, 38
	v_readlane_b32 s23, v223, 39
	v_readlane_b32 s24, v223, 40
	v_readlane_b32 s25, v223, 41
	v_readlane_b32 s26, v223, 42
	v_readlane_b32 s27, v223, 43
	v_readlane_b32 s28, v223, 44
	v_readlane_b32 s29, v223, 45
	v_readlane_b32 s30, v223, 46
	v_readlane_b32 s31, v223, 47
	v_fmac_f32_e32 v224, s16, v176
	v_fmac_f32_e32 v224, s17, v177
	v_fmac_f32_e32 v224, s18, v178
	v_fmac_f32_e32 v224, s19, v179
	v_fmac_f32_e32 v224, s20, v180
	v_fmac_f32_e32 v224, s21, v181
	v_fmac_f32_e32 v224, s22, v182
	v_fmac_f32_e32 v224, s23, v183
	v_fmac_f32_e32 v224, s24, v184
	v_fmac_f32_e32 v224, s25, v185
	v_fmac_f32_e32 v224, s26, v186
	v_fmac_f32_e32 v224, s27, v187
	v_fmac_f32_e32 v224, s28, v188
	v_fmac_f32_e32 v224, s29, v189
	v_fmac_f32_e32 v224, s30, v190
	v_fmac_f32_e32 v224, s31, v191
	v_readlane_b32 s16, v223, 48
	v_readlane_b32 s17, v223, 49
	v_readlane_b32 s18, v223, 50
	v_readlane_b32 s19, v223, 51
	v_readlane_b32 s20, v223, 52
	v_readlane_b32 s21, v223, 53
	v_readlane_b32 s22, v223, 54
	v_readlane_b32 s23, v223, 55
	v_readlane_b32 s24, v223, 56
	v_readlane_b32 s25, v223, 57
	v_readlane_b32 s26, v223, 58
	v_readlane_b32 s27, v223, 59
	v_readlane_b32 s28, v223, 60
	v_readlane_b32 s29, v223, 61
	v_readlane_b32 s30, v223, 62
	v_readlane_b32 s31, v223, 63
	v_fmac_f32_e32 v224, s16, v192
	v_fmac_f32_e32 v224, s17, v193
	v_fmac_f32_e32 v224, s18, v194
	v_fmac_f32_e32 v224, s19, v195
	v_fmac_f32_e32 v224, s20, v196
	v_fmac_f32_e32 v224, s21, v197
	v_fmac_f32_e32 v224, s22, v198
	v_fmac_f32_e32 v224, s23, v199
	v_fmac_f32_e32 v224, s24, v200
	v_fmac_f32_e32 v224, s25, v201
	v_fmac_f32_e32 v224, s26, v202
	v_fmac_f32_e32 v224, s27, v203
	v_fmac_f32_e32 v224, s28, v204
	v_fmac_f32_e32 v224, s29, v205
	v_fmac_f32_e32 v224, s30, v206
	v_fmac_f32_e32 v224, s31, v207
	v_mul_f32_e32 v224, v224, v213
	v_mul_f32_e32 v224, 0.15915494, v224
	v_sin_f32_e32 v225, v224
	s_nop 0
	v_cvt_pk_bf16_f32 v225, v225, v225
	s_lshl_b32 s8, s8, 7
	s_add_u32 s16, s14, s8
	s_addc_u32 s17, s15, 0
	global_store_short v217, v225, s[16:17]
	s_add_i32 s3, s3, vcc_hi
	s_cmp_lt_i32 s3, vcc_lo
	s_cbranch_scc1 .Lmlp_loop
